# v25 with the scan-phase conversion pipelined and fully asynchronous (own-load wait counts depend on hasv; loader waits count the conversion ops out)
# speedup vs baseline: 1.0120x; 1.0017x over previous
.LBB0_208:
	s_cmp_eq_u32 s53, 1
	s_cbranch_scc0 .Lcis_b_done
	s_cmp_eq_u32 s56, 0
	s_cbranch_scc1 .Lcis_pw9
	s_waitcnt vmcnt(11)
	s_branch .Lcis_pwd
.Lcis_pw9:
	s_waitcnt vmcnt(9)
.Lcis_pwd:
	s_cmp_eq_u32 s61, 2
	s_cbranch_scc1 .Lcis_b_flat
	s_cmp_eq_u32 s61, 0
	s_cbranch_scc1 .Lcis_b_nogs
	v_mul_f32_e32 v232, v232, v248
	v_mul_f32_e32 v233, v233, v248
	v_mul_f32_e32 v234, v234, v248
	v_mul_f32_e32 v235, v235, v248
	v_mul_f32_e32 v236, v236, v249
	v_mul_f32_e32 v237, v237, v249
	v_mul_f32_e32 v238, v238, v249
	v_mul_f32_e32 v239, v239, v249
	v_mul_f32_e32 v240, v240, v250
	v_mul_f32_e32 v241, v241, v250
	v_mul_f32_e32 v242, v242, v250
	v_mul_f32_e32 v243, v243, v250
	v_mul_f32_e32 v244, v244, v251
	v_mul_f32_e32 v245, v245, v251
	v_mul_f32_e32 v246, v246, v251
	v_mul_f32_e32 v247, v247, v251

.LBB0_212:
	s_or_b64 exec, exec, s[22:23]
	s_and_b32 s22, s24, 0x800
	s_addk_i32 s24, 0x800
	v_add_u32_e32 v40, s22, v171
	s_add_u32 s20, s20, 32
	ds_read_b64 v[40:41], v40
	s_addc_u32 s21, s21, 0
	s_mov_b64 s[22:23], 0x48000
	s_add_i32 s19, s19, 1
	s_waitcnt lgkmcnt(0)
	v_cvt_pk_bf16_f32 v42, v40, v41
	v_lshl_add_u64 v[40:41], s[14:15], 0, v[148:149]
	v_lshl_add_u64 v[148:149], v[148:149], 0, s[92:93]
	v_lshl_add_u64 v[150:151], v[150:151], 0, s[92:93]
	v_lshl_add_u64 v[154:155], v[154:155], 0, s[22:23]
	s_cmpk_eq_i32 s20, 0xfa0
	global_store_dword v[40:41], v42, off
	s_barrier
	s_cbranch_scc1 .LBB0_214
	s_cmp_eq_u32 s53, 1
	s_cbranch_scc0 .Lcis_w1
	s_cmp_eq_u32 s61, 1
	s_cbranch_scc1 .Lcis_w9
	s_waitcnt vmcnt(5)
	s_branch .Lcis_wd
.Lcis_w9:
	s_waitcnt vmcnt(9)
	s_branch .Lcis_wd
